# fold_uw on f32 MFMA (v_mfma_f32_16x16x4_f32), operands loaded straight to registers, no LDS; on top of p0ada+p0tr+fftb3
# speedup vs baseline: 1.0220x; 1.0075x over previous
.LBB0_172:
	s_cmp_lt_i32 s82, 2
	s_cselect_b64 s[2:3], -1, 0
	s_and_b64 s[6:7], s[2:3], s[0:1]
	s_andn2_b64 vcc, exec, s[6:7]
	s_cbranch_vccnz .LBB0_197
	s_cmpk_gt_i32 s33, 0xff
	s_cbranch_scc1 .LBB0_188
	v_and_b32_e32 v1, 15, v180
	v_lshrrev_b32_e32 v2, 4, v180
	v_lshlrev_b32_e32 v3, 13, v1
	v_lshl_or_b32 v3, v2, 4, v3
	v_lshlrev_b32_e32 v4, 11, v2
	v_lshl_or_b32 v4, v1, 2, v4
	v_lshlrev_b32_e32 v5, 11, v1
	v_lshl_or_b32 v5, v2, 3, v5
	s_mov_b32 s23, s33
.Lfold_task:
	s_lshl_b32 s0, s23, 5
	s_and_b32 s10, s0, 0x3e0
	s_bfe_u32 s14, s23, 0x20005
	s_ashr_i32 s25, s23, 7
	s_lshl_b32 s0, s10, 13
	s_lshl_b32 s1, s14, 9
	s_add_u32 s0, s0, s1
	s_waitcnt lgkmcnt(0)
	s_add_u32 s16, s70, s0
	s_addc_u32 s17, s71, 0
	s_add_u32 s18, s16, 0x20000
	s_addc_u32 s19, s17, 0
	s_lshl_b32 s0, s25, 2
	s_or_b32 s0, s0, s14
	s_lshl_b32 s0, s0, 16
	s_lshl_b32 s1, s92, 6
	s_add_u32 s0, s0, s1
	s_add_u32 s0, s0, 0x180000
	s_add_u32 s20, s80, s0
	s_addc_u32 s21, s81, 0
	s_lshl_b32 s0, s25, 9
	s_lshl_b32 s1, s14, 7
	s_add_u32 s0, s0, s1
	s_lshl_b32 s1, s92, 4
	s_add_u32 s0, s0, s1
	s_lshl_b32 s0, s0, 11
	s_lshl_b32 s1, s10, 1
	s_add_u32 s0, s0, s1
	s_add_u32 s0, s0, 0x600000
	s_add_u32 s8, s80, s0
	s_addc_u32 s9, s81, 0
	global_load_dwordx4 v[16:19], v3, s[16:17]
	global_load_dwordx4 v[48:51], v3, s[18:19]
	global_load_dword v80, v4, s[20:21]
	global_load_dword v81, v4, s[20:21] offset:512
	global_load_dword v82, v4, s[20:21] offset:1024
	global_load_dword v83, v4, s[20:21] offset:1536
	s_add_u32 s20, s20, 0x2000
	s_addc_u32 s21, s21, 0
	global_load_dwordx4 v[20:23], v3, s[16:17] offset:64
	global_load_dwordx4 v[52:55], v3, s[18:19] offset:64
	global_load_dword v84, v4, s[20:21]
	global_load_dword v85, v4, s[20:21] offset:512
	global_load_dword v86, v4, s[20:21] offset:1024
	global_load_dword v87, v4, s[20:21] offset:1536
	s_add_u32 s20, s20, 0x2000
	s_addc_u32 s21, s21, 0
	global_load_dwordx4 v[24:27], v3, s[16:17] offset:128
	global_load_dwordx4 v[56:59], v3, s[18:19] offset:128
	global_load_dword v88, v4, s[20:21]
	global_load_dword v89, v4, s[20:21] offset:512
	global_load_dword v90, v4, s[20:21] offset:1024
	global_load_dword v91, v4, s[20:21] offset:1536
	s_add_u32 s20, s20, 0x2000
	s_addc_u32 s21, s21, 0
	global_load_dwordx4 v[28:31], v3, s[16:17] offset:192
	global_load_dwordx4 v[60:63], v3, s[18:19] offset:192
	global_load_dword v92, v4, s[20:21]
	global_load_dword v93, v4, s[20:21] offset:512
	global_load_dword v94, v4, s[20:21] offset:1024
	global_load_dword v95, v4, s[20:21] offset:1536
	s_add_u32 s20, s20, 0x2000
	s_addc_u32 s21, s21, 0
	global_load_dwordx4 v[32:35], v3, s[16:17] offset:256
	global_load_dwordx4 v[64:67], v3, s[18:19] offset:256
	global_load_dword v96, v4, s[20:21]
	global_load_dword v97, v4, s[20:21] offset:512
	global_load_dword v98, v4, s[20:21] offset:1024
	global_load_dword v99, v4, s[20:21] offset:1536
	s_add_u32 s20, s20, 0x2000
	s_addc_u32 s21, s21, 0
	global_load_dwordx4 v[36:39], v3, s[16:17] offset:320
	global_load_dwordx4 v[68:71], v3, s[18:19] offset:320
	global_load_dword v100, v4, s[20:21]
	global_load_dword v101, v4, s[20:21] offset:512
	global_load_dword v102, v4, s[20:21] offset:1024
	global_load_dword v103, v4, s[20:21] offset:1536
	s_add_u32 s20, s20, 0x2000
	s_addc_u32 s21, s21, 0
	global_load_dwordx4 v[40:43], v3, s[16:17] offset:384
	global_load_dwordx4 v[72:75], v3, s[18:19] offset:384
	global_load_dword v104, v4, s[20:21]
	global_load_dword v105, v4, s[20:21] offset:512
	global_load_dword v106, v4, s[20:21] offset:1024
	global_load_dword v107, v4, s[20:21] offset:1536
	s_add_u32 s20, s20, 0x2000
	s_addc_u32 s21, s21, 0
	global_load_dwordx4 v[44:47], v3, s[16:17] offset:448
	global_load_dwordx4 v[76:79], v3, s[18:19] offset:448
	global_load_dword v108, v4, s[20:21]
	global_load_dword v109, v4, s[20:21] offset:512
	global_load_dword v110, v4, s[20:21] offset:1024
	global_load_dword v111, v4, s[20:21] offset:1536
	s_waitcnt vmcnt(42)
	v_mfma_f32_16x16x4_f32 v[112:115], v16, v80, 0
	v_mfma_f32_16x16x4_f32 v[116:119], v48, v80, 0
	v_mfma_f32_16x16x4_f32 v[112:115], v17, v81, v[112:115]
	v_mfma_f32_16x16x4_f32 v[116:119], v49, v81, v[116:119]
	v_mfma_f32_16x16x4_f32 v[112:115], v18, v82, v[112:115]
	v_mfma_f32_16x16x4_f32 v[116:119], v50, v82, v[116:119]
	v_mfma_f32_16x16x4_f32 v[112:115], v19, v83, v[112:115]
	v_mfma_f32_16x16x4_f32 v[116:119], v51, v83, v[116:119]
	s_waitcnt vmcnt(36)
	v_mfma_f32_16x16x4_f32 v[112:115], v20, v84, v[112:115]
	v_mfma_f32_16x16x4_f32 v[116:119], v52, v84, v[116:119]
	v_mfma_f32_16x16x4_f32 v[112:115], v21, v85, v[112:115]
	v_mfma_f32_16x16x4_f32 v[116:119], v53, v85, v[116:119]
	v_mfma_f32_16x16x4_f32 v[112:115], v22, v86, v[112:115]
	v_mfma_f32_16x16x4_f32 v[116:119], v54, v86, v[116:119]
	v_mfma_f32_16x16x4_f32 v[112:115], v23, v87, v[112:115]
	v_mfma_f32_16x16x4_f32 v[116:119], v55, v87, v[116:119]
	s_waitcnt vmcnt(30)
	v_mfma_f32_16x16x4_f32 v[112:115], v24, v88, v[112:115]
	v_mfma_f32_16x16x4_f32 v[116:119], v56, v88, v[116:119]
	v_mfma_f32_16x16x4_f32 v[112:115], v25, v89, v[112:115]
	v_mfma_f32_16x16x4_f32 v[116:119], v57, v89, v[116:119]
	v_mfma_f32_16x16x4_f32 v[112:115], v26, v90, v[112:115]
	v_mfma_f32_16x16x4_f32 v[116:119], v58, v90, v[116:119]
	v_mfma_f32_16x16x4_f32 v[112:115], v27, v91, v[112:115]
	v_mfma_f32_16x16x4_f32 v[116:119], v59, v91, v[116:119]
	s_waitcnt vmcnt(24)
	v_mfma_f32_16x16x4_f32 v[112:115], v28, v92, v[112:115]
	v_mfma_f32_16x16x4_f32 v[116:119], v60, v92, v[116:119]
	v_mfma_f32_16x16x4_f32 v[112:115], v29, v93, v[112:115]
	v_mfma_f32_16x16x4_f32 v[116:119], v61, v93, v[116:119]
	v_mfma_f32_16x16x4_f32 v[112:115], v30, v94, v[112:115]
	v_mfma_f32_16x16x4_f32 v[116:119], v62, v94, v[116:119]
	v_mfma_f32_16x16x4_f32 v[112:115], v31, v95, v[112:115]
	v_mfma_f32_16x16x4_f32 v[116:119], v63, v95, v[116:119]
	s_waitcnt vmcnt(18)
	v_mfma_f32_16x16x4_f32 v[112:115], v32, v96, v[112:115]
	v_mfma_f32_16x16x4_f32 v[116:119], v64, v96, v[116:119]
	v_mfma_f32_16x16x4_f32 v[112:115], v33, v97, v[112:115]
	v_mfma_f32_16x16x4_f32 v[116:119], v65, v97, v[116:119]
	v_mfma_f32_16x16x4_f32 v[112:115], v34, v98, v[112:115]
	v_mfma_f32_16x16x4_f32 v[116:119], v66, v98, v[116:119]
	v_mfma_f32_16x16x4_f32 v[112:115], v35, v99, v[112:115]
	v_mfma_f32_16x16x4_f32 v[116:119], v67, v99, v[116:119]
	s_waitcnt vmcnt(12)
	v_mfma_f32_16x16x4_f32 v[112:115], v36, v100, v[112:115]
	v_mfma_f32_16x16x4_f32 v[116:119], v68, v100, v[116:119]
	v_mfma_f32_16x16x4_f32 v[112:115], v37, v101, v[112:115]
	v_mfma_f32_16x16x4_f32 v[116:119], v69, v101, v[116:119]
	v_mfma_f32_16x16x4_f32 v[112:115], v38, v102, v[112:115]
	v_mfma_f32_16x16x4_f32 v[116:119], v70, v102, v[116:119]
	v_mfma_f32_16x16x4_f32 v[112:115], v39, v103, v[112:115]
	v_mfma_f32_16x16x4_f32 v[116:119], v71, v103, v[116:119]
	s_waitcnt vmcnt(6)
	v_mfma_f32_16x16x4_f32 v[112:115], v40, v104, v[112:115]
	v_mfma_f32_16x16x4_f32 v[116:119], v72, v104, v[116:119]
	v_mfma_f32_16x16x4_f32 v[112:115], v41, v105, v[112:115]
	v_mfma_f32_16x16x4_f32 v[116:119], v73, v105, v[116:119]
	v_mfma_f32_16x16x4_f32 v[112:115], v42, v106, v[112:115]
	v_mfma_f32_16x16x4_f32 v[116:119], v74, v106, v[116:119]
	v_mfma_f32_16x16x4_f32 v[112:115], v43, v107, v[112:115]
	v_mfma_f32_16x16x4_f32 v[116:119], v75, v107, v[116:119]
	s_waitcnt vmcnt(0)
	v_mfma_f32_16x16x4_f32 v[112:115], v44, v108, v[112:115]
	v_mfma_f32_16x16x4_f32 v[116:119], v76, v108, v[116:119]
	v_mfma_f32_16x16x4_f32 v[112:115], v45, v109, v[112:115]
	v_mfma_f32_16x16x4_f32 v[116:119], v77, v109, v[116:119]
	v_mfma_f32_16x16x4_f32 v[112:115], v46, v110, v[112:115]
	v_mfma_f32_16x16x4_f32 v[116:119], v78, v110, v[116:119]
	v_mfma_f32_16x16x4_f32 v[112:115], v47, v111, v[112:115]
	v_mfma_f32_16x16x4_f32 v[116:119], v79, v111, v[116:119]
	s_nop 7
	s_nop 3
	v_cvt_pk_bf16_f32 v6, v112, v113
	v_cvt_pk_bf16_f32 v7, v114, v115
	v_cvt_pk_bf16_f32 v8, v116, v117
	v_cvt_pk_bf16_f32 v9, v118, v119
	s_add_i32 s23, s23, s84
	s_cmpk_gt_i32 s23, 0xff
	global_store_dwordx2 v5, v[6:7], s[8:9]
	global_store_dwordx2 v5, v[8:9], s[8:9] offset:32
	s_cbranch_scc0 .Lfold_task
